# S5 unit setup: 8 serialized exec-masked C-fragment load blocks merged into one block with 16 loads in flight
# speedup vs baseline: 1.0048x; 1.0048x over previous
.LBB0_483:
	s_or_b64 exec, exec, s[10:11]
	v_mul_f32_e32 v5, v1, v5
	v_mul_f32_e32 v9, 0x3fb8aa3b, v5
	v_fma_f32 v10, v5, s66, -v9
	v_rndne_f32_e32 v11, v9
	v_fmac_f32_e32 v10, 0x32a5705f, v5
	v_sub_f32_e32 v9, v9, v11
	s_mov_b64 s[10:11], s[0:1]
	v_add_f32_e32 v9, v9, v10
	s_mov_b64 s[12:13], s[0:1]
	v_cvt_i32_f32_e32 v10, v11
	v_exp_f32_e32 v9, v9
	s_load_dwordx2 s[10:11], s[10:11], 0x58
	s_load_dwordx2 s[14:15], s[12:13], 0x60
	s_lshl_b64 s[12:13], s[58:59], 12
	v_ldexp_f32 v9, v9, v10
	v_lshl_or_b32 v10, v138, 6, s12
	v_mov_b32_e32 v11, s13
	s_waitcnt lgkmcnt(0)
	v_lshl_add_u64 v[12:13], s[10:11], 0, v[10:11]
	v_lshl_add_u64 v[10:11], s[14:15], 0, v[10:11]
	global_load_dwordx4 v[28:31], v[10:11], off offset:48
	global_load_dwordx4 v[14:17], v[10:11], off offset:32
	global_load_dwordx4 v[62:65], v[12:13], off offset:48
	global_load_dwordx4 v[24:27], v[12:13], off offset:32
	global_load_dwordx4 v[66:69], v[10:11], off offset:16
	global_load_dwordx4 v[58:61], v[10:11], off
	global_load_dwordx4 v[70:73], v[12:13], off offset:16
	global_load_dwordx4 v[74:77], v[12:13], off
	v_cmp_ngt_f32_e32 vcc, s82, v5
	s_brev_b32 s10, 1
	v_and_b32_e32 v121, 31, v129
	v_cndmask_b32_e32 v9, 0, v9, vcc
	v_cmp_nlt_f32_e32 vcc, s83, v5
	v_mul_f32_e32 v5, v6, v6
	v_lshrrev_b32_e32 v136, 5, v138
	v_cndmask_b32_e32 v34, v224, v9, vcc
	v_fmamk_f32 v9, v5, 0xb94c1982, v221
	v_fmaak_f32 v9, v5, v9, 0xbe2aaa9d
	v_mul_f32_e32 v9, v5, v9
	v_fmac_f32_e32 v6, v6, v9
	v_fmamk_f32 v9, v5, 0x37d75334, v222
	v_fmaak_f32 v9, v5, v9, 0x3d2aabf7
	v_fmaak_f32 v9, v5, v9, 0xbf000004
	v_fma_f32 v5, v5, v9, 1.0
	v_and_b32_e32 v9, 1, v4
	v_cmp_eq_u32_e32 vcc, 0, v9
	v_lshlrev_b32_e32 v4, 30, v4
	v_lshlrev_b32_e32 v120, 3, v136
	v_cndmask_b32_e64 v5, -v6, v5, vcc
	v_mul_f32_e32 v6, v8, v8
	v_fmamk_f32 v9, v6, 0xb94c1982, v221
	v_fmaak_f32 v9, v6, v9, 0xbe2aaa9d
	v_mul_f32_e32 v9, v6, v9
	v_fmac_f32_e32 v8, v8, v9
	v_fmamk_f32 v9, v6, 0x37d75334, v222
	v_fmaak_f32 v9, v6, v9, 0x3d2aabf7
	v_fmaak_f32 v9, v6, v9, 0xbf000004
	v_bitop3_b32 v4, v4, v5, s10 bitop3:0x6c
	s_movk_i32 s10, 0x1f8
	v_fma_f32 v6, v6, v9, 1.0
	v_and_b32_e32 v9, 1, v7
	v_lshlrev_b32_e32 v7, 30, v7
	v_cmp_class_f32_e64 vcc, v2, s10
	v_cmp_eq_u32_e64 s[10:11], 0, v9
	v_and_b32_e32 v7, 0x80000000, v7
	v_xor_b32_e32 v2, v3, v2
	v_cndmask_b32_e64 v6, v6, v8, s[10:11]
	v_xor_b32_e32 v2, v2, v7
	v_xor_b32_e32 v2, v2, v6
	v_cndmask_b32_e32 v2, v229, v2, vcc
	v_cndmask_b32_e32 v35, v229, v4, vcc
	v_mul_f32_e32 v124, v34, v2
	v_mov_b32_e32 v4, v1
	v_mov_b32_e32 v5, v0
	v_fma_f32 v2, v34, v35, -1.0
	v_mov_b32_e32 v3, v124
	v_pk_mul_f32 v[4:5], v[4:5], v[2:3]
	v_mov_b32_e32 v3, v1
	v_add_f32_e32 v6, v4, v5
	v_mov_b32_e32 v4, v0
	v_mov_b32_e32 v5, v124
	v_pk_mul_f32 v[4:5], v[0:1], v[4:5]
	v_pk_mul_f32 v[0:1], v[0:1], v[2:3]
	s_nop 0
	v_add_f32_e32 v1, v4, v1
	v_div_scale_f32 v2, s[10:11], v1, v1, v6
	v_rcp_f32_e32 v3, v2
	v_sub_f32_e32 v0, v5, v0
	v_fma_f32 v4, -v2, v3, 1.0
	v_fmac_f32_e32 v3, v4, v3
	v_div_scale_f32 v4, vcc, v6, v1, v6
	v_mul_f32_e32 v7, v4, v3
	v_fma_f32 v8, -v2, v7, v4
	v_fmac_f32_e32 v7, v8, v3
	v_fma_f32 v2, -v2, v7, v4
	v_div_scale_f32 v4, s[10:11], v1, v1, v0
	v_rcp_f32_e32 v5, v4
	v_div_fmas_f32 v2, v2, v3, v7
	v_div_fixup_f32 v32, v2, v1, v6
	v_cmp_gt_u32_e64 s[10:11], 16, v121
	v_fma_f32 v2, -v4, v5, 1.0
	v_fmac_f32_e32 v5, v2, v5
	v_div_scale_f32 v2, vcc, v0, v1, v0
	v_mul_f32_e32 v3, v2, v5
	v_fma_f32 v6, -v4, v3, v2
	v_fmac_f32_e32 v3, v6, v5
	v_fma_f32 v2, -v4, v3, v2
	v_div_fmas_f32 v2, v2, v5, v3
	v_div_fixup_f32 v78, v2, v1, v0
	s_waitcnt vmcnt(3)
	v_pk_mul_f32 v[18:19], v[68:69], v[78:79] op_sel_hi:[1,0]
	v_pk_mul_f32 v[0:1], v[14:15], v[78:79] op_sel_hi:[1,0]
	s_waitcnt vmcnt(1)
	v_pk_fma_f32 v[22:23], v[72:73], v[32:33], v[18:19] op_sel_hi:[1,0,1] neg_lo:[0,0,1] neg_hi:[0,0,1]
	v_pk_mul_f32 v[18:19], v[24:25], v[78:79] op_sel_hi:[1,0]
	v_pk_fma_f32 v[0:1], v[24:25], v[32:33], v[0:1] op_sel_hi:[1,0,1] neg_lo:[0,0,1] neg_hi:[0,0,1]
	v_pk_fma_f32 v[14:15], v[14:15], v[32:33], v[18:19] op_sel_hi:[1,0,1]
	s_waitcnt vmcnt(0)
	v_pk_mul_f32 v[18:19], v[74:75], v[78:79] op_sel_hi:[1,0]
	v_pk_mul_f32 v[4:5], v[16:17], v[78:79] op_sel_hi:[1,0]
	v_pk_fma_f32 v[20:21], v[58:59], v[32:33], v[18:19] op_sel_hi:[1,0,1]
	v_pk_mul_f32 v[18:19], v[26:27], v[78:79] op_sel_hi:[1,0]
	v_pk_mul_f32 v[6:7], v[60:61], v[78:79] op_sel_hi:[1,0]
	v_pk_fma_f32 v[16:17], v[16:17], v[32:33], v[18:19] op_sel_hi:[1,0,1]
	v_pk_mul_f32 v[18:19], v[76:77], v[78:79] op_sel_hi:[1,0]
	v_pk_mul_f32 v[24:25], v[70:71], v[78:79] op_sel_hi:[1,0]
	v_pk_mul_f32 v[2:3], v[58:59], v[78:79] op_sel_hi:[1,0]
	v_pk_fma_f32 v[4:5], v[26:27], v[32:33], v[4:5] op_sel_hi:[1,0,1] neg_lo:[0,0,1] neg_hi:[0,0,1]
	v_pk_fma_f32 v[8:9], v[76:77], v[32:33], v[6:7] op_sel_hi:[1,0,1] neg_lo:[0,0,1] neg_hi:[0,0,1]
	v_pk_mul_f32 v[6:7], v[78:79], v[28:29] op_sel_hi:[0,1]
	v_pk_mul_f32 v[10:11], v[66:67], v[78:79] op_sel_hi:[1,0]
	v_pk_mul_f32 v[12:13], v[78:79], v[30:31] op_sel_hi:[0,1]
	v_pk_fma_f32 v[26:27], v[60:61], v[32:33], v[18:19] op_sel_hi:[1,0,1]
	v_pk_mul_f32 v[18:19], v[32:33], v[28:29] op_sel_hi:[0,1]
	v_pk_fma_f32 v[28:29], v[66:67], v[32:33], v[24:25] op_sel_hi:[1,0,1]
	v_pk_mul_f32 v[24:25], v[32:33], v[30:31] op_sel_hi:[0,1]
	v_pk_mul_f32 v[30:31], v[72:73], v[78:79] op_sel_hi:[1,0]
	v_pk_fma_f32 v[2:3], v[74:75], v[32:33], v[2:3] op_sel_hi:[1,0,1] neg_lo:[0,0,1] neg_hi:[0,0,1]
	v_pk_fma_f32 v[6:7], v[32:33], v[62:63], v[6:7] op_sel_hi:[0,1,1] neg_lo:[0,0,1] neg_hi:[0,0,1]
	v_pk_fma_f32 v[10:11], v[70:71], v[32:33], v[10:11] op_sel_hi:[1,0,1] neg_lo:[0,0,1] neg_hi:[0,0,1]
	v_pk_fma_f32 v[12:13], v[32:33], v[64:65], v[12:13] op_sel_hi:[0,1,1] neg_lo:[0,0,1] neg_hi:[0,0,1]
	v_pk_fma_f32 v[18:19], v[78:79], v[62:63], v[18:19] op_sel_hi:[0,1,1]
	v_pk_fma_f32 v[24:25], v[78:79], v[64:65], v[24:25] op_sel_hi:[0,1,1]
	v_pk_fma_f32 v[30:31], v[68:69], v[32:33], v[30:31] op_sel_hi:[1,0,1]
	ds_bpermute_b32 v36, v235, v0
	ds_bpermute_b32 v38, v235, v1
	ds_bpermute_b32 v37, v235, v2
	ds_bpermute_b32 v39, v235, v3
	ds_bpermute_b32 v40, v235, v4
	ds_bpermute_b32 v41, v235, v5
	ds_bpermute_b32 v42, v235, v8
	ds_bpermute_b32 v43, v235, v9
	ds_bpermute_b32 v44, v235, v6
	ds_bpermute_b32 v46, v235, v7
	ds_bpermute_b32 v45, v235, v10
	ds_bpermute_b32 v47, v235, v11
	ds_bpermute_b32 v48, v235, v12
	ds_bpermute_b32 v49, v235, v13
	ds_bpermute_b32 v52, v235, v22
	ds_bpermute_b32 v56, v235, v23
	ds_bpermute_b32 v50, v235, v14
	ds_bpermute_b32 v53, v235, v15
	ds_bpermute_b32 v51, v235, v20
	ds_bpermute_b32 v54, v235, v21
	ds_bpermute_b32 v55, v235, v16
	ds_bpermute_b32 v58, v235, v17
	ds_bpermute_b32 v57, v235, v26
	ds_bpermute_b32 v59, v235, v27
	ds_bpermute_b32 v60, v235, v18
	ds_bpermute_b32 v62, v235, v19
	ds_bpermute_b32 v61, v235, v28
	ds_bpermute_b32 v63, v235, v29
	ds_bpermute_b32 v107, v235, v24
	ds_bpermute_b32 v109, v235, v25
	ds_bpermute_b32 v108, v235, v30
	ds_bpermute_b32 v110, v235, v31
	v_lshlrev_b32_e32 v32, 6, v121
	v_mov_b32_e32 v64, 0
	v_lshlrev_b32_e32 v192, 2, v32
	v_lshlrev_b32_e32 v32, 2, v120
	v_mov_b32_e32 v65, 0
	v_mov_b32_e32 v66, 0
	v_mov_b32_e32 v67, 0
	v_mov_b32_e32 v68, 0
	v_mov_b32_e32 v69, 0
	v_mov_b32_e32 v70, 0
	v_mov_b32_e32 v71, 0
	v_mov_b32_e32 v72, 0
	v_mov_b32_e32 v73, 0
	v_mov_b32_e32 v74, 0
	v_mov_b32_e32 v75, 0
	v_mov_b32_e32 v76, 0
	v_mov_b32_e32 v77, 0
	v_mov_b32_e32 v78, 0
	v_mov_b32_e32 v79, 0
	v_mov_b32_e32 v80, 0
	v_mov_b32_e32 v81, 0
	v_mov_b32_e32 v82, 0
	v_mov_b32_e32 v83, 0
	v_mov_b32_e32 v84, 0
	v_mov_b32_e32 v85, 0
	v_mov_b32_e32 v86, 0
	v_mov_b32_e32 v87, 0
	v_mov_b32_e32 v88, 0
	v_mov_b32_e32 v89, 0
	v_mov_b32_e32 v90, 0
	v_mov_b32_e32 v91, 0
	v_mov_b32_e32 v92, 0
	v_mov_b32_e32 v93, 0
	v_mov_b32_e32 v94, 0
	v_mov_b32_e32 v95, 0
	s_and_saveexec_b64 s[14:15], s[10:11]
	s_cbranch_execz .LBB0_499
	s_load_dwordx2 s[22:23], s[0:1], 0x68
	s_load_dwordx2 s[24:25], s[0:1], 0x70
	v_mov_b32_e32 v33, v193
	s_waitcnt lgkmcnt(0)
	s_add_u32 s22, s22, s12
	s_addc_u32 s23, s23, s13
	s_add_u32 s24, s24, s12
	s_addc_u32 s25, s25, s13
	v_lshl_add_u64 v[204:205], s[22:23], 0, v[192:193]
	v_lshl_add_u64 v[206:207], s[24:25], 0, v[192:193]
	v_lshl_add_u64 v[204:205], v[204:205], 0, v[32:33]
	v_lshl_add_u64 v[206:207], v[206:207], 0, v[32:33]
	global_load_dwordx4 v[68:71], v[204:205], off
	global_load_dwordx4 v[164:167], v[204:205], off offset:16
	global_load_dwordx4 v[64:67], v[204:205], off offset:64
	global_load_dwordx4 v[168:171], v[204:205], off offset:80
	global_load_dwordx4 v[76:79], v[204:205], off offset:128
	global_load_dwordx4 v[172:175], v[204:205], off offset:144
	global_load_dwordx4 v[72:75], v[204:205], off offset:192
	global_load_dwordx4 v[176:179], v[204:205], off offset:208
	global_load_dwordx4 v[84:87], v[206:207], off
	global_load_dwordx4 v[180:183], v[206:207], off offset:16
	global_load_dwordx4 v[80:83], v[206:207], off offset:64
	global_load_dwordx4 v[184:187], v[206:207], off offset:80
	global_load_dwordx4 v[92:95], v[206:207], off offset:128
	global_load_dwordx4 v[188:191], v[206:207], off offset:144
	global_load_dwordx4 v[88:91], v[206:207], off offset:192
	global_load_dwordx4 v[200:203], v[206:207], off offset:208
	s_waitcnt vmcnt(14)
	v_cvt_pk_bf16_f32 v68, v68, v69
	v_cvt_pk_bf16_f32 v69, v70, v71
	v_cvt_pk_bf16_f32 v70, v164, v165
	v_cvt_pk_bf16_f32 v71, v166, v167
	s_waitcnt vmcnt(12)
	v_cvt_pk_bf16_f32 v64, v64, v65
	v_cvt_pk_bf16_f32 v65, v66, v67
	v_cvt_pk_bf16_f32 v66, v168, v169
	v_cvt_pk_bf16_f32 v67, v170, v171
	s_waitcnt vmcnt(10)
	v_cvt_pk_bf16_f32 v76, v76, v77
	v_cvt_pk_bf16_f32 v77, v78, v79
	v_cvt_pk_bf16_f32 v78, v172, v173
	v_cvt_pk_bf16_f32 v79, v174, v175
	s_waitcnt vmcnt(8)
	v_cvt_pk_bf16_f32 v72, v72, v73
	v_cvt_pk_bf16_f32 v73, v74, v75
	v_cvt_pk_bf16_f32 v74, v176, v177
	v_cvt_pk_bf16_f32 v75, v178, v179
	s_waitcnt vmcnt(6)
	v_xor_b32_e32 v84, 0x80000000, v84
	v_xor_b32_e32 v85, 0x80000000, v85
	v_xor_b32_e32 v86, 0x80000000, v86
	v_xor_b32_e32 v87, 0x80000000, v87
	v_xor_b32_e32 v180, 0x80000000, v180
	v_xor_b32_e32 v181, 0x80000000, v181
	v_xor_b32_e32 v182, 0x80000000, v182
	v_xor_b32_e32 v183, 0x80000000, v183
	v_cvt_pk_bf16_f32 v84, v84, v85
	v_cvt_pk_bf16_f32 v85, v86, v87
	v_cvt_pk_bf16_f32 v86, v180, v181
	v_cvt_pk_bf16_f32 v87, v182, v183
	s_waitcnt vmcnt(4)
	v_xor_b32_e32 v80, 0x80000000, v80
	v_xor_b32_e32 v81, 0x80000000, v81
	v_xor_b32_e32 v82, 0x80000000, v82
	v_xor_b32_e32 v83, 0x80000000, v83
	v_xor_b32_e32 v184, 0x80000000, v184
	v_xor_b32_e32 v185, 0x80000000, v185
	v_xor_b32_e32 v186, 0x80000000, v186
	v_xor_b32_e32 v187, 0x80000000, v187
	v_cvt_pk_bf16_f32 v80, v80, v81
	v_cvt_pk_bf16_f32 v81, v82, v83
	v_cvt_pk_bf16_f32 v82, v184, v185
	v_cvt_pk_bf16_f32 v83, v186, v187
	s_waitcnt vmcnt(2)
	v_xor_b32_e32 v92, 0x80000000, v92
	v_xor_b32_e32 v93, 0x80000000, v93
	v_xor_b32_e32 v94, 0x80000000, v94
	v_xor_b32_e32 v95, 0x80000000, v95
	v_xor_b32_e32 v188, 0x80000000, v188
	v_xor_b32_e32 v189, 0x80000000, v189
	v_xor_b32_e32 v190, 0x80000000, v190
	v_xor_b32_e32 v191, 0x80000000, v191
	v_cvt_pk_bf16_f32 v92, v92, v93
	v_cvt_pk_bf16_f32 v93, v94, v95
	v_cvt_pk_bf16_f32 v94, v188, v189
	v_cvt_pk_bf16_f32 v95, v190, v191
	s_waitcnt vmcnt(0)
	v_xor_b32_e32 v88, 0x80000000, v88
	v_xor_b32_e32 v89, 0x80000000, v89
	v_xor_b32_e32 v90, 0x80000000, v90
	v_xor_b32_e32 v91, 0x80000000, v91
	v_xor_b32_e32 v200, 0x80000000, v200
	v_xor_b32_e32 v201, 0x80000000, v201
	v_xor_b32_e32 v202, 0x80000000, v202
	v_xor_b32_e32 v203, 0x80000000, v203
	v_cvt_pk_bf16_f32 v88, v88, v89
	v_cvt_pk_bf16_f32 v89, v90, v91
	v_cvt_pk_bf16_f32 v90, v200, v201
	v_cvt_pk_bf16_f32 v91, v202, v203
.LBB0_499:
	s_or_b64 exec, exec, s[14:15]
	s_mov_b32 s22, 0
	v_cmp_gt_u32_e32 vcc, 32, v138
	s_mov_b64 s[14:15], s[0:1]
	s_load_dwordx2 s[14:15], s[14:15], 0x78
	s_waitcnt lgkmcnt(0)
	v_cndmask_b32_e32 v3, v38, v3, vcc
	v_cndmask_b32_e32 v2, v36, v2, vcc
	v_cvt_pk_bf16_f32 v96, v2, v3
	v_cndmask_b32_e32 v2, v41, v9, vcc
	v_cndmask_b32_e32 v3, v40, v8, vcc
	v_cvt_pk_bf16_f32 v97, v3, v2
	v_cndmask_b32_e32 v2, v5, v43, vcc
	v_cndmask_b32_e32 v3, v4, v42, vcc
	v_cndmask_b32_e32 v4, v46, v11, vcc
	v_cndmask_b32_e32 v5, v44, v10, vcc
	v_cndmask_b32_e32 v1, v1, v39, vcc
	v_cndmask_b32_e32 v0, v0, v37, vcc
	v_cvt_pk_bf16_f32 v98, v5, v4
	v_cndmask_b32_e32 v4, v7, v47, vcc
	v_cndmask_b32_e32 v5, v6, v45, vcc
	v_cndmask_b32_e32 v6, v49, v23, vcc
	v_cndmask_b32_e32 v7, v48, v22, vcc
	v_cvt_pk_bf16_f32 v99, v7, v6
	v_cndmask_b32_e32 v6, v13, v56, vcc
	v_cndmask_b32_e32 v7, v12, v52, vcc
	v_cvt_pk_bf16_f32 v100, v0, v1
	v_cvt_pk_bf16_f32 v101, v3, v2
	v_cndmask_b32_e32 v0, v53, v21, vcc
	v_cndmask_b32_e32 v1, v50, v20, vcc
	v_cndmask_b32_e32 v2, v58, v27, vcc
	v_cndmask_b32_e32 v3, v55, v26, vcc
	v_cvt_pk_bf16_f32 v103, v7, v6
	v_cvt_pk_bf16_f32 v104, v1, v0
	v_cndmask_b32_e32 v0, v15, v54, vcc
	v_cndmask_b32_e32 v1, v14, v51, vcc
	v_cvt_pk_bf16_f32 v105, v3, v2
	v_cndmask_b32_e32 v2, v17, v59, vcc
	v_cndmask_b32_e32 v3, v16, v57, vcc
	v_cndmask_b32_e32 v6, v109, v31, vcc
	v_cndmask_b32_e32 v7, v107, v30, vcc
	s_add_u32 s12, s20, 0x16200000
	v_cvt_pk_bf16_f32 v107, v7, v6
	v_cndmask_b32_e32 v7, v24, v108, vcc
	v_cvt_pk_bf16_f32 v108, v1, v0
	v_cvt_pk_bf16_f32 v109, v3, v2
	s_addc_u32 s13, s21, 0
	v_lshlrev_b32_e32 v0, 2, v129
	v_lshrrev_b32_e32 v2, 1, v129
	s_lshl_b32 s23, s58, 4
	s_lshr_b32 s4, s4, 5
	s_ashr_i32 s20, s27, 6
	v_and_b32_e32 v0, 16, v0
	v_and_b32_e32 v1, 3, v129
	v_and_b32_e32 v2, 12, v2
	v_and_or_b32 v192, v129, 15, s23
	s_andn2_b32 s27, s27, 63
	s_lshl_b32 s21, s4, 11
	v_or3_b32 v128, v0, v1, v2
	v_lshl_add_u64 v[0:1], v[192:193], 2, s[14:15]
	s_ashr_i32 s14, s27, 31
	s_add_u32 s15, s27, s21
	global_load_dword v137, v[0:1], off
	v_or_b32_e32 v2, s15, v128
	v_mov_b64_e32 v[0:1], s[12:13]
	s_addc_u32 s23, s14, 0
	v_mad_u64_u32 v[0:1], s[14:15], v2, s55, v[0:1]
	v_mad_i32_i24 v1, s23, v225, v1
	s_lshl_b32 s58, s26, 5
	v_lshl_add_u64 v[0:1], v[0:1], 0, s[58:59]
	v_lshlrev_b32_e32 v192, 1, v120
	v_cvt_pk_bf16_f32 v102, v5, v4
	v_cndmask_b32_e32 v4, v62, v29, vcc
	v_cndmask_b32_e32 v5, v60, v28, vcc
	v_lshl_add_u64 v[0:1], v[0:1], 0, v[192:193]
	s_mov_b64 s[24:25], 0x1200
	v_cvt_pk_bf16_f32 v106, v5, v4
	v_cndmask_b32_e32 v4, v19, v63, vcc
	v_cndmask_b32_e32 v5, v18, v61, vcc
	v_cndmask_b32_e32 v6, v25, v110, vcc
	v_lshl_add_u64 v[116:117], v[0:1], 0, s[24:25]
	v_add_co_u32_e32 v0, vcc, s3, v0
	v_mul_f32_e32 v126, v34, v35
	s_nop 0
	v_addc_co_u32_e32 v1, vcc, 0, v1, vcc
	global_load_dwordx4 v[112:115], v[0:1], off offset:512
	v_mov_b32_e32 v130, 0
	v_cvt_pk_bf16_f32 v110, v5, v4
	v_cvt_pk_bf16_f32 v111, v7, v6
	s_lshl_b32 s14, s26, 4
	v_lshl_add_u32 v139, v138, 2, 0
	v_mov_b32_e32 v127, v126
	v_mov_b32_e32 v125, v124
	v_mov_b32_e32 v118, v126
	v_mov_b32_e32 v119, v124
	v_mov_b32_e32 v122, v124
	v_mov_b32_e32 v123, v126
	s_mov_b32 s15, 0
	v_mov_b32_e32 v131, v130
	s_branch .LBB0_501
